# second half of each task's cache-shift copy moved behind the arrivals of the P1->P2 and P3->P4 grid barriers (waves 1-7)
# baseline (speedup 1.0000x reference)
.LBB0_337:
	s_or_b64 exec, exec, s[4:5]
	s_lshr_b32 s0, s97, 6
	s_cmp_eq_u32 s0, 0
	s_cbranch_scc1 .Lw2_skip
	s_mul_i32 s1, s2, 7
	s_add_i32 s0, s0, s1
	s_add_i32 s0, s0, -1
	v_mbcnt_lo_u32_b32 v106, -1, 0
	v_mbcnt_hi_u32_b32 v106, -1, v106
	v_mov_b32_e32 v108, s0
	v_lshlrev_b32_e32 v106, 4, v106
	v_mov_b32_e32 v107, 0x80403
	v_min_u32_e32 v101, 0x5fff, v108
	v_add_u32_e32 v108, 0x700, v108
	v_lshrrev_b32_e32 v102, 2, v101
	v_and_b32_e32 v101, 3, v101
	v_lshl_add_u32 v101, v102, 3, v101
	v_add_u32_e32 v101, 4, v101
	v_mul_hi_u32 v102, v101, v107
	v_mul_u32_u24_e32 v103, 0x1ff0, v102
	v_and_b32_e32 v104, 7, v102
	v_sub_u32_e32 v103, v101, v103
	v_lshrrev_b32_e32 v102, 3, v102
	v_lshlrev_b32_e32 v104, 23, v104
	v_cmp_ne_u32_e32 vcc, 0, v102
	v_lshl_add_u32 v103, v103, 10, v104
	v_add_u32_e32 v103, v103, v106
	v_lshl_add_u32 v110, v102, 26, v103
	v_add_u32_e32 v103, 0x4000, v103
	v_add_u32_e32 v110, 0x605e000, v110
	s_cbranch_vccnz .Lw2_v0
	global_load_dwordx4 v[170:173], v103, s[48:49] nt
	s_branch .Lw2_d0
.Lw2_v0:
	global_load_dwordx4 v[170:173], v103, s[50:51] nt
.Lw2_d0:
	v_min_u32_e32 v101, 0x5fff, v108
	v_add_u32_e32 v108, 0x700, v108
	v_lshrrev_b32_e32 v102, 2, v101
	v_and_b32_e32 v101, 3, v101
	v_lshl_add_u32 v101, v102, 3, v101
	v_add_u32_e32 v101, 4, v101
	v_mul_hi_u32 v102, v101, v107
	v_mul_u32_u24_e32 v103, 0x1ff0, v102
	v_and_b32_e32 v104, 7, v102
	v_sub_u32_e32 v103, v101, v103
	v_lshrrev_b32_e32 v102, 3, v102
	v_lshlrev_b32_e32 v104, 23, v104
	v_cmp_ne_u32_e32 vcc, 0, v102
	v_lshl_add_u32 v103, v103, 10, v104
	v_add_u32_e32 v103, v103, v106
	v_lshl_add_u32 v111, v102, 26, v103
	v_add_u32_e32 v103, 0x4000, v103
	v_add_u32_e32 v111, 0x605e000, v111
	s_cbranch_vccnz .Lw2_v1
	global_load_dwordx4 v[174:177], v103, s[48:49] nt
	s_branch .Lw2_d1
.Lw2_v1:
	global_load_dwordx4 v[174:177], v103, s[50:51] nt
.Lw2_d1:
	v_min_u32_e32 v101, 0x5fff, v108
	v_add_u32_e32 v108, 0x700, v108
	v_lshrrev_b32_e32 v102, 2, v101
	v_and_b32_e32 v101, 3, v101
	v_lshl_add_u32 v101, v102, 3, v101
	v_add_u32_e32 v101, 4, v101
	v_mul_hi_u32 v102, v101, v107
	v_mul_u32_u24_e32 v103, 0x1ff0, v102
	v_and_b32_e32 v104, 7, v102
	v_sub_u32_e32 v103, v101, v103
	v_lshrrev_b32_e32 v102, 3, v102
	v_lshlrev_b32_e32 v104, 23, v104
	v_cmp_ne_u32_e32 vcc, 0, v102
	v_lshl_add_u32 v103, v103, 10, v104
	v_add_u32_e32 v103, v103, v106
	v_lshl_add_u32 v112, v102, 26, v103
	v_add_u32_e32 v103, 0x4000, v103
	v_add_u32_e32 v112, 0x605e000, v112
	s_cbranch_vccnz .Lw2_v2
	global_load_dwordx4 v[178:181], v103, s[48:49] nt
	s_branch .Lw2_d2
.Lw2_v2:
	global_load_dwordx4 v[178:181], v103, s[50:51] nt
.Lw2_d2:
	v_min_u32_e32 v101, 0x5fff, v108
	v_add_u32_e32 v108, 0x700, v108
	v_lshrrev_b32_e32 v102, 2, v101
	v_and_b32_e32 v101, 3, v101
	v_lshl_add_u32 v101, v102, 3, v101
	v_add_u32_e32 v101, 4, v101
	v_mul_hi_u32 v102, v101, v107
	v_mul_u32_u24_e32 v103, 0x1ff0, v102
	v_and_b32_e32 v104, 7, v102
	v_sub_u32_e32 v103, v101, v103
	v_lshrrev_b32_e32 v102, 3, v102
	v_lshlrev_b32_e32 v104, 23, v104
	v_cmp_ne_u32_e32 vcc, 0, v102
	v_lshl_add_u32 v103, v103, 10, v104
	v_add_u32_e32 v103, v103, v106
	v_lshl_add_u32 v113, v102, 26, v103
	v_add_u32_e32 v103, 0x4000, v103
	v_add_u32_e32 v113, 0x605e000, v113
	s_cbranch_vccnz .Lw2_v3
	global_load_dwordx4 v[182:185], v103, s[48:49] nt
	s_branch .Lw2_d3
.Lw2_v3:
	global_load_dwordx4 v[182:185], v103, s[50:51] nt
.Lw2_d3:
	v_min_u32_e32 v101, 0x5fff, v108
	v_add_u32_e32 v108, 0x700, v108
	v_lshrrev_b32_e32 v102, 2, v101
	v_and_b32_e32 v101, 3, v101
	v_lshl_add_u32 v101, v102, 3, v101
	v_add_u32_e32 v101, 4, v101
	v_mul_hi_u32 v102, v101, v107
	v_mul_u32_u24_e32 v103, 0x1ff0, v102
	v_and_b32_e32 v104, 7, v102
	v_sub_u32_e32 v103, v101, v103
	v_lshrrev_b32_e32 v102, 3, v102
	v_lshlrev_b32_e32 v104, 23, v104
	v_cmp_ne_u32_e32 vcc, 0, v102
	v_lshl_add_u32 v103, v103, 10, v104
	v_add_u32_e32 v103, v103, v106
	v_lshl_add_u32 v114, v102, 26, v103
	v_add_u32_e32 v103, 0x4000, v103
	v_add_u32_e32 v114, 0x605e000, v114
	s_cbranch_vccnz .Lw2_v4
	global_load_dwordx4 v[186:189], v103, s[48:49] nt
	s_branch .Lw2_d4
.Lw2_v4:
	global_load_dwordx4 v[186:189], v103, s[50:51] nt
.Lw2_d4:
	v_min_u32_e32 v101, 0x5fff, v108
	v_add_u32_e32 v108, 0x700, v108
	v_lshrrev_b32_e32 v102, 2, v101
	v_and_b32_e32 v101, 3, v101
	v_lshl_add_u32 v101, v102, 3, v101
	v_add_u32_e32 v101, 4, v101
	v_mul_hi_u32 v102, v101, v107
	v_mul_u32_u24_e32 v103, 0x1ff0, v102
	v_and_b32_e32 v104, 7, v102
	v_sub_u32_e32 v103, v101, v103
	v_lshrrev_b32_e32 v102, 3, v102
	v_lshlrev_b32_e32 v104, 23, v104
	v_cmp_ne_u32_e32 vcc, 0, v102
	v_lshl_add_u32 v103, v103, 10, v104
	v_add_u32_e32 v103, v103, v106
	v_lshl_add_u32 v115, v102, 26, v103
	v_add_u32_e32 v103, 0x4000, v103
	v_add_u32_e32 v115, 0x605e000, v115
	s_cbranch_vccnz .Lw2_v5
	global_load_dwordx4 v[190:193], v103, s[48:49] nt
	s_branch .Lw2_d5
.Lw2_v5:
	global_load_dwordx4 v[190:193], v103, s[50:51] nt
.Lw2_d5:
	v_min_u32_e32 v101, 0x5fff, v108
	v_add_u32_e32 v108, 0x700, v108
	v_lshrrev_b32_e32 v102, 2, v101
	v_and_b32_e32 v101, 3, v101
	v_lshl_add_u32 v101, v102, 3, v101
	v_add_u32_e32 v101, 4, v101
	v_mul_hi_u32 v102, v101, v107
	v_mul_u32_u24_e32 v103, 0x1ff0, v102
	v_and_b32_e32 v104, 7, v102
	v_sub_u32_e32 v103, v101, v103
	v_lshrrev_b32_e32 v102, 3, v102
	v_lshlrev_b32_e32 v104, 23, v104
	v_cmp_ne_u32_e32 vcc, 0, v102
	v_lshl_add_u32 v103, v103, 10, v104
	v_add_u32_e32 v103, v103, v106
	v_lshl_add_u32 v116, v102, 26, v103
	v_add_u32_e32 v103, 0x4000, v103
	v_add_u32_e32 v116, 0x605e000, v116
	s_cbranch_vccnz .Lw2_v6
	global_load_dwordx4 v[194:197], v103, s[48:49] nt
	s_branch .Lw2_d6
.Lw2_v6:
	global_load_dwordx4 v[194:197], v103, s[50:51] nt
.Lw2_d6:
	v_min_u32_e32 v101, 0x5fff, v108
	v_add_u32_e32 v108, 0x700, v108
	v_lshrrev_b32_e32 v102, 2, v101
	v_and_b32_e32 v101, 3, v101
	v_lshl_add_u32 v101, v102, 3, v101
	v_add_u32_e32 v101, 4, v101
	v_mul_hi_u32 v102, v101, v107
	v_mul_u32_u24_e32 v103, 0x1ff0, v102
	v_and_b32_e32 v104, 7, v102
	v_sub_u32_e32 v103, v101, v103
	v_lshrrev_b32_e32 v102, 3, v102
	v_lshlrev_b32_e32 v104, 23, v104
	v_cmp_ne_u32_e32 vcc, 0, v102
	v_lshl_add_u32 v103, v103, 10, v104
	v_add_u32_e32 v103, v103, v106
	v_lshl_add_u32 v117, v102, 26, v103
	v_add_u32_e32 v103, 0x4000, v103
	v_add_u32_e32 v117, 0x605e000, v117
	s_cbranch_vccnz .Lw2_v7
	global_load_dwordx4 v[198:201], v103, s[48:49] nt
	s_branch .Lw2_d7
.Lw2_v7:
	global_load_dwordx4 v[198:201], v103, s[50:51] nt
.Lw2_d7:
	v_min_u32_e32 v101, 0x5fff, v108
	v_add_u32_e32 v108, 0x700, v108
	v_lshrrev_b32_e32 v102, 2, v101
	v_and_b32_e32 v101, 3, v101
	v_lshl_add_u32 v101, v102, 3, v101
	v_add_u32_e32 v101, 4, v101
	v_mul_hi_u32 v102, v101, v107
	v_mul_u32_u24_e32 v103, 0x1ff0, v102
	v_and_b32_e32 v104, 7, v102
	v_sub_u32_e32 v103, v101, v103
	v_lshrrev_b32_e32 v102, 3, v102
	v_lshlrev_b32_e32 v104, 23, v104
	v_cmp_ne_u32_e32 vcc, 0, v102
	v_lshl_add_u32 v103, v103, 10, v104
	v_add_u32_e32 v103, v103, v106
	v_lshl_add_u32 v118, v102, 26, v103
	v_add_u32_e32 v103, 0x4000, v103
	v_add_u32_e32 v118, 0x605e000, v118
	s_cbranch_vccnz .Lw2_v8
	global_load_dwordx4 v[202:205], v103, s[48:49] nt
	s_branch .Lw2_d8
.Lw2_v8:
	global_load_dwordx4 v[202:205], v103, s[50:51] nt
.Lw2_d8:
	v_min_u32_e32 v101, 0x5fff, v108
	v_add_u32_e32 v108, 0x700, v108
	v_lshrrev_b32_e32 v102, 2, v101
	v_and_b32_e32 v101, 3, v101
	v_lshl_add_u32 v101, v102, 3, v101
	v_add_u32_e32 v101, 4, v101
	v_mul_hi_u32 v102, v101, v107
	v_mul_u32_u24_e32 v103, 0x1ff0, v102
	v_and_b32_e32 v104, 7, v102
	v_sub_u32_e32 v103, v101, v103
	v_lshrrev_b32_e32 v102, 3, v102
	v_lshlrev_b32_e32 v104, 23, v104
	v_cmp_ne_u32_e32 vcc, 0, v102
	v_lshl_add_u32 v103, v103, 10, v104
	v_add_u32_e32 v103, v103, v106
	v_lshl_add_u32 v119, v102, 26, v103
	v_add_u32_e32 v103, 0x4000, v103
	v_add_u32_e32 v119, 0x605e000, v119
	s_cbranch_vccnz .Lw2_v9
	global_load_dwordx4 v[206:209], v103, s[48:49] nt
	s_branch .Lw2_d9
.Lw2_v9:
	global_load_dwordx4 v[206:209], v103, s[50:51] nt
.Lw2_d9:
	v_min_u32_e32 v101, 0x5fff, v108
	v_add_u32_e32 v108, 0x700, v108
	v_lshrrev_b32_e32 v102, 2, v101
	v_and_b32_e32 v101, 3, v101
	v_lshl_add_u32 v101, v102, 3, v101
	v_add_u32_e32 v101, 4, v101
	v_mul_hi_u32 v102, v101, v107
	v_mul_u32_u24_e32 v103, 0x1ff0, v102
	v_and_b32_e32 v104, 7, v102
	v_sub_u32_e32 v103, v101, v103
	v_lshrrev_b32_e32 v102, 3, v102
	v_lshlrev_b32_e32 v104, 23, v104
	v_cmp_ne_u32_e32 vcc, 0, v102
	v_lshl_add_u32 v103, v103, 10, v104
	v_add_u32_e32 v103, v103, v106
	v_lshl_add_u32 v120, v102, 26, v103
	v_add_u32_e32 v103, 0x4000, v103
	v_add_u32_e32 v120, 0x605e000, v120
	s_cbranch_vccnz .Lw2_v10
	global_load_dwordx4 v[210:213], v103, s[48:49] nt
	s_branch .Lw2_d10
.Lw2_v10:
	global_load_dwordx4 v[210:213], v103, s[50:51] nt
.Lw2_d10:
	v_min_u32_e32 v101, 0x5fff, v108
	v_add_u32_e32 v108, 0x700, v108
	v_lshrrev_b32_e32 v102, 2, v101
	v_and_b32_e32 v101, 3, v101
	v_lshl_add_u32 v101, v102, 3, v101
	v_add_u32_e32 v101, 4, v101
	v_mul_hi_u32 v102, v101, v107
	v_mul_u32_u24_e32 v103, 0x1ff0, v102
	v_and_b32_e32 v104, 7, v102
	v_sub_u32_e32 v103, v101, v103
	v_lshrrev_b32_e32 v102, 3, v102
	v_lshlrev_b32_e32 v104, 23, v104
	v_cmp_ne_u32_e32 vcc, 0, v102
	v_lshl_add_u32 v103, v103, 10, v104
	v_add_u32_e32 v103, v103, v106
	v_lshl_add_u32 v121, v102, 26, v103
	v_add_u32_e32 v103, 0x4000, v103
	v_add_u32_e32 v121, 0x605e000, v121
	s_cbranch_vccnz .Lw2_v11
	global_load_dwordx4 v[214:217], v103, s[48:49] nt
	s_branch .Lw2_d11
.Lw2_v11:
	global_load_dwordx4 v[214:217], v103, s[50:51] nt
.Lw2_d11:
	v_min_u32_e32 v101, 0x5fff, v108
	v_add_u32_e32 v108, 0x700, v108
	v_lshrrev_b32_e32 v102, 2, v101
	v_and_b32_e32 v101, 3, v101
	v_lshl_add_u32 v101, v102, 3, v101
	v_add_u32_e32 v101, 4, v101
	v_mul_hi_u32 v102, v101, v107
	v_mul_u32_u24_e32 v103, 0x1ff0, v102
	v_and_b32_e32 v104, 7, v102
	v_sub_u32_e32 v103, v101, v103
	v_lshrrev_b32_e32 v102, 3, v102
	v_lshlrev_b32_e32 v104, 23, v104
	v_cmp_ne_u32_e32 vcc, 0, v102
	v_lshl_add_u32 v103, v103, 10, v104
	v_add_u32_e32 v103, v103, v106
	v_lshl_add_u32 v122, v102, 26, v103
	v_add_u32_e32 v103, 0x4000, v103
	v_add_u32_e32 v122, 0x605e000, v122
	s_cbranch_vccnz .Lw2_v12
	global_load_dwordx4 v[218:221], v103, s[48:49] nt
	s_branch .Lw2_d12
.Lw2_v12:
	global_load_dwordx4 v[218:221], v103, s[50:51] nt
.Lw2_d12:
	v_min_u32_e32 v101, 0x5fff, v108
	v_add_u32_e32 v108, 0x700, v108
	v_lshrrev_b32_e32 v102, 2, v101
	v_and_b32_e32 v101, 3, v101
	v_lshl_add_u32 v101, v102, 3, v101
	v_add_u32_e32 v101, 4, v101
	v_mul_hi_u32 v102, v101, v107
	v_mul_u32_u24_e32 v103, 0x1ff0, v102
	v_and_b32_e32 v104, 7, v102
	v_sub_u32_e32 v103, v101, v103
	v_lshrrev_b32_e32 v102, 3, v102
	v_lshlrev_b32_e32 v104, 23, v104
	v_cmp_ne_u32_e32 vcc, 0, v102
	v_lshl_add_u32 v103, v103, 10, v104
	v_add_u32_e32 v103, v103, v106
	v_lshl_add_u32 v123, v102, 26, v103
	v_add_u32_e32 v103, 0x4000, v103
	v_add_u32_e32 v123, 0x605e000, v123
	s_cbranch_vccnz .Lw2_v13
	global_load_dwordx4 v[222:225], v103, s[48:49] nt
	s_branch .Lw2_d13
.Lw2_v13:
	global_load_dwordx4 v[222:225], v103, s[50:51] nt
.Lw2_d13:
	s_waitcnt vmcnt(13)
	global_store_dwordx4 v110, v[170:173], s[66:67] nt
	s_waitcnt vmcnt(13)
	global_store_dwordx4 v111, v[174:177], s[66:67] nt
	s_waitcnt vmcnt(13)
	global_store_dwordx4 v112, v[178:181], s[66:67] nt
	s_waitcnt vmcnt(13)
	global_store_dwordx4 v113, v[182:185], s[66:67] nt
	s_waitcnt vmcnt(13)
	global_store_dwordx4 v114, v[186:189], s[66:67] nt
	s_waitcnt vmcnt(13)
	global_store_dwordx4 v115, v[190:193], s[66:67] nt
	s_waitcnt vmcnt(13)
	global_store_dwordx4 v116, v[194:197], s[66:67] nt
	s_waitcnt vmcnt(13)
	global_store_dwordx4 v117, v[198:201], s[66:67] nt
	s_waitcnt vmcnt(13)
	global_store_dwordx4 v118, v[202:205], s[66:67] nt
	s_waitcnt vmcnt(13)
	global_store_dwordx4 v119, v[206:209], s[66:67] nt
	s_waitcnt vmcnt(13)
	global_store_dwordx4 v120, v[210:213], s[66:67] nt
	s_waitcnt vmcnt(13)
	global_store_dwordx4 v121, v[214:217], s[66:67] nt
	s_waitcnt vmcnt(13)
	global_store_dwordx4 v122, v[218:221], s[66:67] nt
	s_waitcnt vmcnt(13)
	global_store_dwordx4 v123, v[222:225], s[66:67] nt
.Lw2_skip:
	s_add_u32 s30, s92, 0xa800000
	s_addc_u32 s31, s93, 0
	s_cmpk_lt_i32 s33, 0x100
	s_cselect_b64 s[4:5], -1, 0
	s_cmpk_gt_i32 s33, 0xff
	s_mov_b32 s58, s80
	v_readlane_b32 s59, v239, 2
	s_waitcnt lgkmcnt(0)
	s_barrier
	v_mbcnt_lo_u32_b32 v170, -1, 0
	v_mbcnt_hi_u32_b32 v170, -1, v170
	s_cbranch_scc1 .LBB0_377
	s_mul_i32 s0, s81, 0x1200
	s_add_i32 s74, s0, 0
	s_mov_b32 s11, 0
	s_add_i32 s72, s74, 0x12800
	s_lshl_b32 s73, s81, 1
	s_add_i32 s74, s74, 0x1b800
	s_movk_i32 s75, 0x3000
	v_mov_b32_e32 v145, 0
	s_movk_i32 s76, 0x90
	v_mov_b32_e32 v171, 0xff800000
	s_mov_b32 s77, 0x3e38aa3b
	s_movk_i32 s82, 0x1000
	s_mov_b32 s83, s33
	s_branch .LBB0_340

.LBB0_344:
	s_or_b32 s14, s0, s73
	s_or_b32 s0, s0, s87
	s_add_i32 s0, s0, s85
	s_lshl_b32 s12, s0, 9
	s_cmpk_gt_i32 s0, 0x1fef
	s_cselect_b64 s[18:19], -1, 0
	s_add_i32 s13, s12, 0xffc02000
	s_and_b64 s[0:1], s[18:19], exec
	s_cselect_b32 s15, s13, s12
	s_mul_hi_i32 s0, s15, 0x80402011
	s_add_i32 s0, s0, s15
	s_lshr_b32 s1, s0, 31
	s_ashr_i32 s0, s0, 18
	s_add_i32 s16, s0, s1
	s_add_i32 s17, s16, 1
	s_and_b64 s[12:13], s[18:19], exec
	v_mbcnt_lo_u32_b32 v172, -1, 0
	v_mbcnt_hi_u32_b32 v172, -1, v172
	s_cselect_b32 s12, s51, s49
	s_cselect_b32 s13, s50, s48
	s_and_b32 s1, s14, s88
	s_lshr_b32 s14, s14, s87
	v_ashrrev_i32_e32 v36, 3, v172
	s_or_b32 s1, s1, s84
	s_lshl_b32 s14, s14, s89
	v_subrev_u32_e32 v37, 64, v36
	s_add_i32 s1, s1, s14
	v_lshlrev_b32_e32 v37, s87, v37
	v_lshlrev_b32_e32 v1, 4, v172
	v_add_u32_e32 v37, s1, v37
	v_and_b32_e32 v41, 0x70, v1
	v_max_i32_e32 v37, 0, v37
	v_lshl_or_b32 v163, v37, 7, v41
	v_subrev_u32_e32 v37, 56, v36
	v_lshlrev_b32_e32 v37, s87, v37
	v_add_u32_e32 v37, s1, v37
	v_max_i32_e32 v37, 0, v37
	v_lshl_or_b32 v165, v37, 7, v41
	v_subrev_u32_e32 v37, 48, v36
	v_lshlrev_b32_e32 v37, s87, v37
	v_add_u32_e32 v37, s1, v37
	v_max_i32_e32 v37, 0, v37
	v_lshl_or_b32 v167, v37, 7, v41
	v_subrev_u32_e32 v37, 40, v36
	v_lshlrev_b32_e32 v37, s87, v37
	v_add_u32_e32 v37, s1, v37
	v_max_i32_e32 v37, 0, v37
	v_lshl_or_b32 v186, v37, 7, v41
	v_subrev_u32_e32 v37, 32, v36
	v_lshlrev_b32_e32 v37, s87, v37
	v_add_u32_e32 v37, s1, v37
	v_max_i32_e32 v37, 0, v37
	v_lshl_or_b32 v144, v37, 7, v41
	v_subrev_u32_e32 v37, 24, v36
	v_lshlrev_b32_e32 v37, s87, v37
	v_add_u32_e32 v37, s1, v37
	v_max_i32_e32 v37, 0, v37
	v_lshl_or_b32 v154, v37, 7, v41
	v_add_lshl_u32 v37, v36, -16, s87
	v_add_u32_e32 v37, s1, v37
	v_max_i32_e32 v37, 0, v37
	v_lshl_or_b32 v156, v37, 7, v41
	v_add_lshl_u32 v37, v36, -8, s87
	v_add_u32_e32 v37, s1, v37
	v_max_i32_e32 v37, 0, v37
	v_lshl_or_b32 v158, v37, 7, v41
	v_lshlrev_b32_e32 v37, s87, v36
	v_add_u32_e32 v37, s1, v37
	v_max_i32_e32 v37, 0, v37
	v_lshl_or_b32 v160, v37, 7, v41
	v_add_lshl_u32 v37, v36, 8, s87
	v_add_u32_e32 v37, s1, v37
	v_max_i32_e32 v37, 0, v37
	v_lshl_or_b32 v162, v37, 7, v41
	v_add_lshl_u32 v37, v36, 16, s87
	v_add_u32_e32 v37, s1, v37
	v_and_b32_e32 v176, 31, v172
	v_max_i32_e32 v37, 0, v37
	v_lshlrev_b32_e32 v0, s87, v176
	v_lshl_or_b32 v164, v37, 7, v41
	v_add_lshl_u32 v37, v36, 24, s87
	s_mul_i32 s0, s17, 0x7fc00
	v_add_u32_e32 v174, s1, v0
	v_add_u32_e32 v37, s1, v37
	v_add_u32_e32 v187, s15, v172
	v_ashrrev_i32_e32 v173, 5, v172
	v_add_u32_e32 v0, s34, v174
	v_max_i32_e32 v37, 0, v37
	v_mov_b32_e32 v188, s17
	v_mov_b32_e32 v189, s16
	v_cmp_gt_i32_e32 vcc, s0, v187
	v_mul_lo_u32 v0, v0, s75
	v_lshlrev_b32_e32 v40, 4, v173
	v_lshl_or_b32 v166, v37, 7, v41
	v_cndmask_b32_e32 v37, v188, v189, vcc
	v_lshlrev_b32_e32 v38, 4, v187
	v_add3_u32 v0, v40, s10, v0
	v_lshl_add_u32 v190, v37, 14, v38
	v_add_u32_e32 v37, 64, v187
	v_add_u32_e32 v0, 0xffffff80, v36
	v_add_u32_e32 v8, 0xffffff90, v36
	v_add_u32_e32 v20, 0xffffffa0, v36
	v_add_u32_e32 v28, 0xffffffb0, v36
	v_cmp_gt_i32_e32 vcc, s0, v37
	v_lshlrev_b32_e32 v0, s87, v0
	v_lshlrev_b32_e32 v8, s87, v8
	v_lshlrev_b32_e32 v20, s87, v20
	v_lshlrev_b32_e32 v28, s87, v28
	v_cndmask_b32_e32 v38, v188, v189, vcc
	v_lshlrev_b32_e32 v37, 4, v37
	v_add_u32_e32 v0, s1, v0
	v_add_u32_e32 v8, s1, v8
	v_add_u32_e32 v20, s1, v20
	v_add_u32_e32 v28, s1, v28
	v_lshl_add_u32 v191, v38, 14, v37
	v_add_u32_e32 v37, 0x80, v187
	v_max_i32_e32 v0, 0, v0
	v_max_i32_e32 v8, 0, v8
	v_max_i32_e32 v20, 0, v20
	v_max_i32_e32 v28, 0, v28
	v_cmp_gt_i32_e32 vcc, s0, v37
	v_lshl_or_b32 v124, v0, 7, v41
	v_add_u32_e32 v0, 0xffffff88, v36
	v_lshl_or_b32 v126, v8, 7, v41
	v_add_u32_e32 v8, 0xffffff98, v36
	v_lshl_or_b32 v155, v20, 7, v41
	v_add_u32_e32 v20, 0xffffffa8, v36
	v_lshl_or_b32 v159, v28, 7, v41
	v_add_u32_e32 v28, 0xffffffb8, v36
	v_cndmask_b32_e32 v38, v188, v189, vcc
	v_lshlrev_b32_e32 v37, 4, v37
	v_lshlrev_b32_e32 v0, s87, v0
	v_lshlrev_b32_e32 v8, s87, v8
	v_lshlrev_b32_e32 v20, s87, v20
	v_lshlrev_b32_e32 v28, s87, v28
	v_lshl_add_u32 v192, v38, 14, v37
	v_add_u32_e32 v37, 0xc0, v187
	s_add_u32 s36, s13, 0x4000
	v_add_u32_e32 v0, s1, v0
	v_add_u32_e32 v8, s1, v8
	v_add_u32_e32 v20, s1, v20
	v_add_u32_e32 v28, s1, v28
	v_cmp_gt_i32_e32 vcc, s0, v37
	s_addc_u32 s37, s12, 0
	v_max_i32_e32 v0, 0, v0
	v_max_i32_e32 v8, 0, v8
	v_max_i32_e32 v20, 0, v20
	v_max_i32_e32 v28, 0, v28
	v_cndmask_b32_e32 v38, v188, v189, vcc
	v_lshlrev_b32_e32 v37, 4, v37
	v_lshl_or_b32 v125, v0, 7, v41
	global_load_dwordx4 v[0:3], v124, s[40:41]
	global_load_dwordx4 v[4:7], v125, s[40:41]
	v_lshl_or_b32 v127, v8, 7, v41
	global_load_dwordx4 v[8:11], v126, s[40:41]
	global_load_dwordx4 v[12:15], v127, s[40:41]
	v_lshl_or_b32 v157, v20, 7, v41
	global_load_dwordx4 v[20:23], v155, s[40:41]
	global_load_dwordx4 v[24:27], v157, s[40:41]
	v_lshl_or_b32 v161, v28, 7, v41
	global_load_dwordx4 v[28:31], v159, s[40:41]
	global_load_dwordx4 v[32:35], v161, s[40:41]
	global_load_dwordx4 v[48:51], v163, s[40:41]
	global_load_dwordx4 v[52:55], v165, s[40:41]
	global_load_dwordx4 v[56:59], v167, s[40:41]
	global_load_dwordx4 v[60:63], v186, s[40:41]
	global_load_dwordx4 v[92:95], v154, s[40:41]
	global_load_dwordx4 v[96:99], v156, s[40:41]
	global_load_dwordx4 v[100:103], v158, s[40:41]
	global_load_dwordx4 v[104:107], v160, s[40:41]
	global_load_dwordx4 v[108:111], v162, s[40:41]
	global_load_dwordx4 v[112:115], v164, s[40:41]
	global_load_dwordx4 v[116:119], v144, s[40:41]
	global_load_dwordx4 v[120:123], v166, s[40:41]
	global_load_dwordx4 v[146:149], v190, s[36:37] nt
	global_load_dwordx4 v[150:153], v191, s[36:37] nt
	v_lshl_add_u32 v193, v38, 14, v37
	global_load_dwordx4 v[178:181], v192, s[36:37] nt
	global_load_dwordx4 v[182:185], v193, s[36:37] nt
	s_and_b64 s[12:13], s[18:19], exec
	s_mov_b32 s12, 0xa05e000
	s_cselect_b32 s12, s12, 0x605e000
	s_add_u32 s18, s66, s12
	v_lshlrev_b32_e32 v177, 2, v173
	s_addc_u32 s19, s67, 0
	v_mul_lo_u32 v43, v36, s76
	v_add_u32_e32 v168, s72, v41
	v_add_u32_e32 v44, 0x480, v43
	v_add_u32_e32 v45, 0x900, v43
	v_add_u32_e32 v46, 0xd80, v43
	v_mul_u32_u24_e32 v42, 0x90, v176
	v_add_u32_e32 v175, v168, v43
	v_add_u32_e32 v128, v168, v44
	v_add_u32_e32 v129, v168, v45
	v_add_u32_e32 v130, v168, v46
	s_waitcnt vmcnt(23)
	ds_write_b128 v175, v[0:3]
	s_waitcnt vmcnt(22)
	ds_write_b128 v128, v[4:7]
	s_waitcnt vmcnt(21)
	ds_write_b128 v129, v[8:11]
	s_waitcnt vmcnt(20)
	ds_write_b128 v130, v[12:15]
	v_add3_u32 v131, s72, v42, v40
	ds_read_b128 v[0:3], v131
	ds_read_b128 v[36:39], v131 offset:32
	s_waitcnt lgkmcnt(1)
	v_mfma_f32_32x32x16_bf16 v[0:15], v[0:3], v[240:243], 0
	v_add_u32_e32 v47, s74, v41
	v_add_u32_e32 v132, v47, v43
	v_add3_u32 v133, s74, v42, v40
	ds_read_b128 v[40:43], v131 offset:96
	v_add_u32_e32 v134, v47, v44
	v_add_u32_e32 v135, v47, v45
	v_add_u32_e32 v136, v47, v46
	s_waitcnt lgkmcnt(1)
	v_mfma_f32_32x32x16_bf16 v[0:15], v[36:39], v[244:247], v[0:15]
	ds_read_b128 v[36:39], v131 offset:64
	s_waitcnt vmcnt(19)
	ds_write_b128 v132, v[20:23]
	s_waitcnt vmcnt(18)
	ds_write_b128 v134, v[24:27]
	s_waitcnt vmcnt(17)
	ds_write_b128 v135, v[28:31]
	s_waitcnt vmcnt(16)
	ds_write_b128 v136, v[32:35]
	ds_read_b128 v[20:23], v133
	s_waitcnt lgkmcnt(5)
	v_mfma_f32_32x32x16_bf16 v[0:15], v[36:39], v[248:251], v[0:15]
	v_mfma_f32_32x32x16_bf16 v[0:15], v[40:43], v[252:255], v[0:15]
	s_waitcnt lgkmcnt(0)
	v_mfma_f32_32x32x16_bf16 v[32:47], v[20:23], v[240:243], 0
	ds_read_b128 v[20:23], v133 offset:32
	s_waitcnt lgkmcnt(0)
	v_mfma_f32_32x32x16_bf16 v[32:47], v[20:23], v[244:247], v[32:47]
	ds_read_b128 v[20:23], v133 offset:64
	s_waitcnt lgkmcnt(0)
	v_mfma_f32_32x32x16_bf16 v[32:47], v[20:23], v[248:251], v[32:47]
	ds_read_b128 v[20:23], v133 offset:96
	s_waitcnt vmcnt(15)
	ds_write_b128 v175, v[48:51]
	s_waitcnt vmcnt(14)
	ds_write_b128 v128, v[52:55]
	s_waitcnt vmcnt(13)
	ds_write_b128 v129, v[56:59]
	s_waitcnt vmcnt(12)
	ds_write_b128 v130, v[60:63]
	s_waitcnt lgkmcnt(4)
	v_mfma_f32_32x32x16_bf16 v[32:47], v[20:23], v[252:255], v[32:47]
	ds_read_b128 v[20:23], v131
	s_waitcnt lgkmcnt(0)
	v_mfma_f32_32x32x16_bf16 v[64:79], v[20:23], v[240:243], 0
	ds_read_b128 v[20:23], v131 offset:32
	s_waitcnt lgkmcnt(0)
	v_mfma_f32_32x32x16_bf16 v[64:79], v[20:23], v[244:247], v[64:79]
	ds_read_b128 v[20:23], v131 offset:64
	s_waitcnt lgkmcnt(0)
	v_mfma_f32_32x32x16_bf16 v[64:79], v[20:23], v[248:251], v[64:79]
	ds_read_b128 v[20:23], v131 offset:96
	s_waitcnt vmcnt(5)
	ds_write_b128 v132, v[116:119]
	ds_write_b128 v134, v[92:95]
	ds_write_b128 v135, v[96:99]
	ds_write_b128 v136, v[100:103]
	s_waitcnt lgkmcnt(4)
	v_mfma_f32_32x32x16_bf16 v[64:79], v[20:23], v[252:255], v[64:79]
	ds_read_b128 v[20:23], v133
	s_waitcnt lgkmcnt(0)
	v_mfma_f32_32x32x16_bf16 v[48:63], v[20:23], v[240:243], 0
	ds_read_b128 v[20:23], v133 offset:32
	s_waitcnt lgkmcnt(0)
	v_mfma_f32_32x32x16_bf16 v[48:63], v[20:23], v[244:247], v[48:63]
	ds_read_b128 v[20:23], v133 offset:64
	s_waitcnt lgkmcnt(0)
	v_mfma_f32_32x32x16_bf16 v[48:63], v[20:23], v[248:251], v[48:63]
	ds_read_b128 v[20:23], v133 offset:96
	ds_write_b128 v175, v[104:107]
	ds_write_b128 v128, v[108:111]
	ds_write_b128 v129, v[112:115]
	s_waitcnt vmcnt(4)
	ds_write_b128 v130, v[120:123]
	ds_read_b128 v[92:95], v131 offset:32
	s_waitcnt lgkmcnt(5)
	v_mfma_f32_32x32x16_bf16 v[48:63], v[20:23], v[252:255], v[48:63]
	ds_read_b128 v[20:23], v131
	s_waitcnt lgkmcnt(0)
	v_mfma_f32_32x32x16_bf16 v[16:31], v[20:23], v[240:243], 0
	v_mfma_f32_32x32x16_bf16 v[16:31], v[92:95], v[244:247], v[16:31]
	ds_read_b128 v[88:91], v131 offset:64
	s_waitcnt lgkmcnt(0)
	v_mfma_f32_32x32x16_bf16 v[16:31], v[88:91], v[248:251], v[16:31]
	ds_read_b128 v[84:87], v131 offset:96
	s_waitcnt lgkmcnt(0)
	v_mfma_f32_32x32x16_bf16 v[16:31], v[84:87], v[252:255], v[16:31]
	global_load_dwordx4 v[140:143], v124, s[42:43]
	global_load_dwordx4 v[136:139], v125, s[42:43]
	global_load_dwordx4 v[132:135], v126, s[42:43]
	global_load_dwordx4 v[128:131], v127, s[42:43]
	global_load_dwordx4 v[112:115], v155, s[42:43]
	global_load_dwordx4 v[116:119], v157, s[42:43]
	global_load_dwordx4 v[120:123], v159, s[42:43]
	s_nop 0
	global_load_dwordx4 v[124:127], v161, s[42:43]
	global_load_dwordx4 v[96:99], v163, s[42:43]
	global_load_dwordx4 v[100:103], v165, s[42:43]
	global_load_dwordx4 v[104:107], v167, s[42:43]
	global_load_dwordx4 v[108:111], v186, s[42:43]
	v_add_u32_e32 v80, 0x100, v187
	v_cmp_gt_i32_e32 vcc, s0, v80
	v_lshlrev_b32_e32 v80, 4, v80
	s_waitcnt vmcnt(15)
	global_store_dwordx4 v190, v[146:149], s[18:19] nt
	s_waitcnt vmcnt(15)
	global_store_dwordx4 v191, v[150:153], s[18:19] nt
	s_waitcnt vmcnt(15)
	global_store_dwordx4 v192, v[178:181], s[18:19] nt
	s_waitcnt vmcnt(15)
	global_store_dwordx4 v193, v[182:185], s[18:19] nt
	v_cndmask_b32_e32 v81, v188, v189, vcc
	v_lshl_add_u32 v146, v81, 14, v80
	v_add_u32_e32 v80, 0x140, v187
	v_cmp_gt_i32_e32 vcc, s0, v80
	v_add_u32_e32 v88, 0x180, v187
	v_lshlrev_b32_e32 v80, 4, v80
	v_cndmask_b32_e32 v81, v188, v189, vcc
	v_cmp_gt_i32_e32 vcc, s0, v88
	v_lshlrev_b32_e32 v88, 4, v88
	v_lshl_add_u32 v148, v81, 14, v80
	v_cndmask_b32_e32 v89, v188, v189, vcc
	v_lshl_add_u32 v150, v89, 14, v88
	v_add_u32_e32 v88, 0x1c0, v187
	v_cmp_gt_i32_e32 vcc, s0, v88
	v_lshlrev_b32_e32 v88, 4, v88
	v_cndmask_b32_e32 v89, v188, v189, vcc
	v_lshl_add_u32 v152, v89, 14, v88
	s_add_i32 s13, s86, 1
	s_cmp_lg_u32 s56, 0
	s_cselect_b32 s12, s86, s13
	s_cselect_b32 s14, 1, 0
	s_min_i32 s12, s12, 2
	s_lshl_b32 s13, s12, 1
	s_or_b32 s14, s14, s73
	s_lshl_b32 s15, -1, s13
	s_andn2_b32 s15, s14, s15
	s_or_b32 s15, s15, s84
	s_lshr_b32 s14, s14, s13
	s_add_i32 s17, s13, 5
	s_lshl_b32 s14, s14, s17
	s_add_i32 s15, s15, s14
	s_add_i32 s15, s15, s34
	v_lshlrev_b32_e32 v194, s13, v176
	v_add_u32_e32 v194, s15, v194
	v_mul_lo_u32 v194, v194, s75
	v_lshlrev_b32_e32 v195, 4, v173
	v_add3_u32 v194, v195, s10, v194
	global_load_dwordx4 v[240:243], v194, s[28:29]
	global_load_dwordx4 v[244:247], v194, s[28:29] offset:32
	global_load_dwordx4 v[248:251], v194, s[28:29] offset:64
	global_load_dwordx4 v[252:255], v194, s[28:29] offset:96
	s_ashr_i32 s0, s1, s87
	s_sub_i32 s1, 0x80, s0
	v_max_i32_e32 v147, s1, v176
	v_sub_u32_e32 v147, v147, v177
	v_cmp_gt_i32_e32 vcc, 1, v147
	s_sub_i32 s1, 0x7f, s0
	s_ashr_i32 s1, s1, 5
	v_cndmask_b32_e32 v192, v171, v0, vcc
	v_cmp_gt_i32_e32 vcc, 2, v147
	s_cmpk_lt_i32 s0, 0x80
	s_cselect_b32 s0, s1, -1
	v_cndmask_b32_e32 v190, v171, v1, vcc
	v_cmp_gt_i32_e32 vcc, 3, v147
	s_mov_b32 s1, 0xff800000
	v_max3_f32 v0, v192, s1, v190
	v_cndmask_b32_e32 v193, v171, v2, vcc
	v_cmp_gt_i32_e32 vcc, 4, v147
	s_cmp_lt_i32 s0, 1
	s_mov_b64 s[36:37], -1
	v_cndmask_b32_e32 v191, v171, v3, vcc
	v_cmp_gt_i32_e32 vcc, 9, v147
	v_max3_f32 v0, v0, v193, v191
	s_nop 0
	v_cndmask_b32_e32 v189, v171, v4, vcc
	v_cmp_gt_i32_e32 vcc, 10, v147
	s_nop 1
	v_cndmask_b32_e32 v187, v171, v5, vcc
	v_cmp_gt_i32_e32 vcc, 11, v147
	v_max3_f32 v0, v0, v189, v187
	s_nop 0
	v_cndmask_b32_e32 v188, v171, v6, vcc
	v_cmp_gt_i32_e32 vcc, 12, v147
	s_nop 1
	v_cndmask_b32_e32 v186, v171, v7, vcc
	v_cmp_gt_i32_e32 vcc, 17, v147
	v_max3_f32 v0, v0, v188, v186
	s_nop 0
	v_cndmask_b32_e32 v185, v171, v8, vcc
	v_cmp_gt_i32_e32 vcc, 18, v147
	s_nop 1
	v_cndmask_b32_e32 v183, v171, v9, vcc
	v_cmp_gt_i32_e32 vcc, 19, v147
	v_max3_f32 v0, v0, v185, v183
	s_nop 0
	v_cndmask_b32_e32 v184, v171, v10, vcc
	v_cmp_gt_i32_e32 vcc, 20, v147
	s_nop 1
	v_cndmask_b32_e32 v182, v171, v11, vcc
	v_cmp_gt_i32_e32 vcc, 25, v147
	v_max3_f32 v0, v0, v184, v182
	s_nop 0
	v_cndmask_b32_e32 v181, v171, v12, vcc
	v_cmp_gt_i32_e32 vcc, 26, v147
	s_nop 1
	v_cndmask_b32_e32 v179, v171, v13, vcc
	v_cmp_gt_i32_e32 vcc, 27, v147
	v_max3_f32 v0, v0, v181, v179
	s_nop 0
	v_cndmask_b32_e32 v180, v171, v14, vcc
	v_cmp_gt_i32_e32 vcc, 28, v147
	s_nop 1
	v_cndmask_b32_e32 v178, v171, v15, vcc
	v_max3_f32 v149, v0, v180, v178
	s_cbranch_scc1 .LBB0_346
	v_cmp_gt_i32_e32 vcc, 33, v147
	s_nop 1
	v_cndmask_b32_e32 v0, v171, v32, vcc
	v_cmp_gt_i32_e32 vcc, 34, v147
	s_nop 1
	v_cndmask_b32_e32 v1, v171, v33, vcc
	v_cmp_gt_i32_e32 vcc, 35, v147
	v_max3_f32 v4, v149, v0, v1
	s_nop 0
	v_cndmask_b32_e32 v2, v171, v34, vcc
	v_cmp_gt_i32_e32 vcc, 36, v147
	s_nop 1
	v_cndmask_b32_e32 v3, v171, v35, vcc
	v_cmp_gt_i32_e32 vcc, 41, v147
	v_max3_f32 v6, v4, v2, v3
	s_nop 0
	v_cndmask_b32_e32 v4, v171, v36, vcc
	v_cmp_gt_i32_e32 vcc, 42, v147
	s_nop 1
	v_cndmask_b32_e32 v5, v171, v37, vcc
	v_cmp_gt_i32_e32 vcc, 43, v147
	v_max3_f32 v8, v6, v4, v5
	s_nop 0
	v_cndmask_b32_e32 v6, v171, v38, vcc
	v_cmp_gt_i32_e32 vcc, 44, v147
	s_nop 1
	v_cndmask_b32_e32 v7, v171, v39, vcc
	v_cmp_gt_i32_e32 vcc, 49, v147
	v_max3_f32 v10, v8, v6, v7
	s_nop 0
	v_cndmask_b32_e32 v8, v171, v40, vcc
	v_cmp_gt_i32_e32 vcc, 50, v147
	s_nop 1
	v_cndmask_b32_e32 v9, v171, v41, vcc
	v_cmp_gt_i32_e32 vcc, 51, v147
	v_max3_f32 v12, v10, v8, v9
	s_nop 0
	v_cndmask_b32_e32 v10, v171, v42, vcc
	v_cmp_gt_i32_e32 vcc, 52, v147
	s_nop 1
	v_cndmask_b32_e32 v11, v171, v43, vcc
	v_cmp_gt_i32_e32 vcc, 57, v147
	v_max3_f32 v14, v12, v10, v11
	s_nop 0
	v_cndmask_b32_e32 v12, v171, v44, vcc
	v_cmp_gt_i32_e32 vcc, 58, v147
	s_nop 1
	v_cndmask_b32_e32 v13, v171, v45, vcc
	v_cmp_gt_i32_e32 vcc, 59, v147
	v_max3_f32 v151, v14, v12, v13
	s_nop 0
	v_cndmask_b32_e32 v14, v171, v46, vcc
	v_cmp_gt_i32_e32 vcc, 60, v147
	s_nop 1
	v_cndmask_b32_e32 v15, v171, v47, vcc
	v_max3_f32 v151, v151, v14, v15
	s_cbranch_execnz .LBB0_348
	s_branch .LBB0_347

.LBB0_356:
	v_and_b32_e32 v49, 16, v172
	v_lshlrev_b32_e32 v50, 2, v172
	v_and_or_b32 v49, v50, 12, v49
	v_or_b32_e32 v50, 0x80, v176
	v_sub_u32_e32 v50, v50, v177
	s_movk_i32 s0, 0x7f
	v_cmp_lt_i32_e32 vcc, s0, v50
	s_movk_i32 s0, 0x80
	v_lshrrev_b32_e32 v48, 2, v172
	v_cndmask_b32_e32 v16, v171, v16, vcc
	v_cmp_lt_i32_e32 vcc, s0, v50
	s_movk_i32 s0, 0x81
	v_and_or_b32 v48, v48, 3, v177
	v_cndmask_b32_e32 v17, v171, v17, vcc
	v_cmp_lt_i32_e32 vcc, s0, v50
	s_movk_i32 s0, 0x82
	v_mov_b32_e32 v155, v145
	v_cndmask_b32_e32 v18, v171, v18, vcc
	v_cmp_lt_i32_e32 vcc, s0, v50
	s_movk_i32 s0, 0x87
	v_mov_b32_e32 v157, v145
	v_cndmask_b32_e32 v19, v171, v19, vcc
	v_cmp_lt_i32_e32 vcc, s0, v50
	s_movk_i32 s0, 0x88
	v_mov_b32_e32 v159, v145
	v_cndmask_b32_e32 v20, v171, v20, vcc
	v_cmp_lt_i32_e32 vcc, s0, v50
	s_movk_i32 s0, 0x89
	v_mov_b32_e32 v161, v145
	v_cndmask_b32_e32 v21, v171, v21, vcc
	v_cmp_lt_i32_e32 vcc, s0, v50
	s_movk_i32 s0, 0x8a
	v_mov_b32_e32 v163, v145
	v_cndmask_b32_e32 v22, v171, v22, vcc
	v_cmp_lt_i32_e32 vcc, s0, v50
	s_movk_i32 s0, 0x8f
	v_mov_b32_e32 v165, v145
	v_cndmask_b32_e32 v23, v171, v23, vcc
	v_cmp_lt_i32_e32 vcc, s0, v50
	s_movk_i32 s0, 0x91
	v_mov_b32_e32 v167, v145
	v_cndmask_b32_e32 v24, v171, v24, vcc
	v_cmp_lt_i32_e32 vcc, s76, v50
	v_mov_b32_e32 v147, v145
	v_mov_b32_e32 v149, v145
	v_cndmask_b32_e32 v25, v171, v25, vcc
	v_cmp_lt_i32_e32 vcc, s0, v50
	s_movk_i32 s0, 0x92
	v_mov_b32_e32 v151, v145
	v_cndmask_b32_e32 v26, v171, v26, vcc
	v_cmp_lt_i32_e32 vcc, s0, v50
	s_movk_i32 s0, 0x97
	v_mov_b32_e32 v153, v145
	v_cndmask_b32_e32 v27, v171, v27, vcc
	v_cmp_lt_i32_e32 vcc, s0, v50
	s_movk_i32 s0, 0x98
	v_mul_lo_u32 v48, v48, s76
	v_cndmask_b32_e32 v28, v171, v28, vcc
	v_cmp_lt_i32_e32 vcc, s0, v50
	s_movk_i32 s0, 0x99
	v_lshlrev_b32_e32 v49, 1, v49
	v_cndmask_b32_e32 v29, v171, v29, vcc
	v_cmp_lt_i32_e32 vcc, s0, v50
	s_movk_i32 s0, 0x9a
	s_nop 0
	v_cndmask_b32_e32 v30, v171, v30, vcc
	v_cmp_lt_i32_e32 vcc, s0, v50
	v_max3_f32 v50, v70, v16, v17
	v_max3_f32 v50, v50, v18, v19
	v_max3_f32 v50, v50, v20, v21
	v_max3_f32 v50, v50, v22, v23
	v_max3_f32 v50, v50, v24, v25
	v_max3_f32 v50, v50, v26, v27
	v_cndmask_b32_e32 v31, v171, v31, vcc
	v_max3_f32 v50, v50, v28, v29
	v_max3_f32 v50, v50, v30, v31
	v_mov_b32_e32 v51, v50
	s_nop 1
	v_permlane32_swap_b32_e32 v50, v51
	v_max_f32_e32 v51, v51, v51
	v_max_f32_e32 v50, v50, v50
	v_max_f32_e32 v70, v50, v51
	v_mul_f32_e32 v50, 0x3e38aa3b, v70
	v_fma_f32 v51, v192, s77, -v50
	v_exp_f32_e32 v51, v51
	v_fma_f32 v52, v190, s77, -v50
	v_exp_f32_e32 v52, v52
	v_fma_f32 v53, v193, s77, -v50
	v_exp_f32_e32 v53, v53
	v_fma_f32 v54, v191, s77, -v50
	v_exp_f32_e32 v54, v54
	v_fma_f32 v56, v189, s77, -v50
	v_add_f32_e32 v55, 0, v51
	v_exp_f32_e32 v56, v56
	v_fma_f32 v57, v187, s77, -v50
	v_add_f32_e32 v55, v52, v55
	v_exp_f32_e32 v57, v57
	v_fma_f32 v58, v188, s77, -v50
	v_add_f32_e32 v55, v53, v55
	v_exp_f32_e32 v58, v58
	v_fma_f32 v59, v186, s77, -v50
	v_add_f32_e32 v55, v54, v55
	v_exp_f32_e32 v59, v59
	v_fma_f32 v60, v185, s77, -v50
	v_add_f32_e32 v55, v56, v55
	v_exp_f32_e32 v60, v60
	v_fma_f32 v61, v183, s77, -v50
	v_add_f32_e32 v55, v57, v55
	v_exp_f32_e32 v61, v61
	v_fma_f32 v62, v184, s77, -v50
	v_add_f32_e32 v55, v58, v55
	v_exp_f32_e32 v62, v62
	v_fma_f32 v63, v182, s77, -v50
	v_add_f32_e32 v55, v59, v55
	v_exp_f32_e32 v63, v63
	v_fma_f32 v176, v181, s77, -v50
	v_add_f32_e32 v55, v60, v55
	v_exp_f32_e32 v193, v176
	v_fma_f32 v176, v179, s77, -v50
	v_add_f32_e32 v55, v61, v55
	v_exp_f32_e32 v195, v176
	v_fma_f32 v176, v180, s77, -v50
	v_add_f32_e32 v55, v62, v55
	v_exp_f32_e32 v196, v176
	v_fma_f32 v176, v178, s77, -v50
	v_add_f32_e32 v55, v63, v55
	v_exp_f32_e32 v197, v176
	v_fma_f32 v0, v0, s77, -v50
	v_add_f32_e32 v55, v193, v55
	v_exp_f32_e32 v198, v0
	v_fma_f32 v0, v1, s77, -v50
	v_add_f32_e32 v55, v195, v55
	v_exp_f32_e32 v199, v0
	v_fma_f32 v0, v2, s77, -v50
	v_add_f32_e32 v55, v196, v55
	v_exp_f32_e32 v200, v0
	v_fma_f32 v0, v3, s77, -v50
	v_add_f32_e32 v55, v197, v55
	v_exp_f32_e32 v201, v0
	v_fma_f32 v1, v4, s77, -v50
	v_add_f32_e32 v0, v198, v55
	v_exp_f32_e32 v202, v1
	v_fma_f32 v1, v5, s77, -v50
	v_add_f32_e32 v0, v199, v0
	v_exp_f32_e32 v203, v1
	v_fma_f32 v1, v6, s77, -v50
	v_add_f32_e32 v0, v200, v0
	v_exp_f32_e32 v204, v1
	v_fma_f32 v1, v7, s77, -v50
	v_add_f32_e32 v0, v201, v0
	v_exp_f32_e32 v205, v1
	v_fma_f32 v1, v8, s77, -v50
	v_add_f32_e32 v0, v202, v0
	v_exp_f32_e32 v206, v1
	v_fma_f32 v1, v9, s77, -v50
	v_add_f32_e32 v0, v203, v0
	v_exp_f32_e32 v207, v1
	v_fma_f32 v1, v10, s77, -v50
	v_add_f32_e32 v0, v204, v0
	v_exp_f32_e32 v208, v1
	v_fma_f32 v1, v11, s77, -v50
	v_add_f32_e32 v0, v205, v0
	v_exp_f32_e32 v209, v1
	v_fma_f32 v1, v12, s77, -v50
	v_add_f32_e32 v0, v206, v0
	v_exp_f32_e32 v210, v1
	v_fma_f32 v1, v13, s77, -v50
	v_add_f32_e32 v0, v207, v0
	v_exp_f32_e32 v211, v1
	v_fma_f32 v1, v14, s77, -v50
	v_add_f32_e32 v0, v208, v0
	v_exp_f32_e32 v212, v1
	v_fma_f32 v1, v15, s77, -v50
	v_add_f32_e32 v0, v209, v0
	v_exp_f32_e32 v213, v1
	v_fma_f32 v1, v32, s77, -v50
	v_add_f32_e32 v0, v210, v0
	v_exp_f32_e32 v214, v1
	v_fma_f32 v1, v33, s77, -v50
	v_add_f32_e32 v0, v211, v0
	v_exp_f32_e32 v215, v1
	v_fma_f32 v1, v34, s77, -v50
	v_add_f32_e32 v0, v212, v0
	v_exp_f32_e32 v216, v1
	v_fma_f32 v1, v35, s77, -v50
	v_add_f32_e32 v0, v213, v0
	v_exp_f32_e32 v217, v1
	v_fma_f32 v1, v36, s77, -v50
	v_add_f32_e32 v0, v214, v0
	v_exp_f32_e32 v218, v1
	v_fma_f32 v1, v37, s77, -v50
	v_add_f32_e32 v0, v215, v0
	v_exp_f32_e32 v219, v1
	v_fma_f32 v1, v38, s77, -v50
	v_add_f32_e32 v0, v216, v0
	v_exp_f32_e32 v220, v1
	v_fma_f32 v1, v39, s77, -v50
	v_add_f32_e32 v0, v217, v0
	v_exp_f32_e32 v221, v1
	v_fma_f32 v1, v40, s77, -v50
	v_add_f32_e32 v0, v218, v0
	v_exp_f32_e32 v222, v1
	v_fma_f32 v1, v41, s77, -v50
	v_add_f32_e32 v0, v219, v0
	v_exp_f32_e32 v223, v1
	v_fma_f32 v1, v42, s77, -v50
	v_add_f32_e32 v0, v220, v0
	v_exp_f32_e32 v224, v1
	v_fma_f32 v1, v43, s77, -v50
	v_add_f32_e32 v0, v221, v0
	v_exp_f32_e32 v225, v1
	v_fma_f32 v1, v44, s77, -v50
	v_add_f32_e32 v0, v222, v0
	v_exp_f32_e32 v226, v1
	v_fma_f32 v1, v45, s77, -v50
	v_add_f32_e32 v0, v223, v0
	v_exp_f32_e32 v227, v1
	v_fma_f32 v1, v46, s77, -v50
	v_add_f32_e32 v0, v224, v0
	v_exp_f32_e32 v228, v1
	v_fma_f32 v1, v47, s77, -v50
	v_add_f32_e32 v0, v225, v0
	v_exp_f32_e32 v229, v1
	v_fma_f32 v1, v64, s77, -v50
	v_add_f32_e32 v0, v226, v0
	v_exp_f32_e32 v230, v1
	v_fma_f32 v1, v65, s77, -v50
	v_add_f32_e32 v0, v227, v0
	v_exp_f32_e32 v231, v1
	v_fma_f32 v1, v66, s77, -v50
	v_add_f32_e32 v0, v228, v0
	v_exp_f32_e32 v232, v1
	v_fma_f32 v1, v68, s77, -v50
	v_add_f32_e32 v0, v229, v0
	v_exp_f32_e32 v233, v1
	v_fma_f32 v1, v67, s77, -v50
	v_add_f32_e32 v0, v230, v0
	v_exp_f32_e32 v234, v1
	v_fma_f32 v1, v69, s77, -v50
	v_add_f32_e32 v0, v231, v0
	v_exp_f32_e32 v235, v1
	v_fma_f32 v1, v71, s77, -v50
	v_add_f32_e32 v0, v232, v0
	v_exp_f32_e32 v236, v1
	v_fma_f32 v1, v73, s77, -v50
	v_add_f32_e32 v0, v233, v0
	v_exp_f32_e32 v237, v1
	v_fma_f32 v1, v72, s77, -v50
	v_add_f32_e32 v0, v234, v0
	v_exp_f32_e32 v186, v1
	v_fma_f32 v1, v74, s77, -v50
	v_add_f32_e32 v0, v235, v0
	v_exp_f32_e32 v187, v1
	v_fma_f32 v1, v75, s77, -v50
	v_add_f32_e32 v0, v236, v0
	v_exp_f32_e32 v188, v1
	v_fma_f32 v1, v77, s77, -v50
	v_add_f32_e32 v0, v237, v0
	v_exp_f32_e32 v189, v1
	v_fma_f32 v1, v76, s77, -v50
	v_add_f32_e32 v0, v186, v0
	v_exp_f32_e32 v190, v1
	v_fma_f32 v1, v78, s77, -v50
	v_add_f32_e32 v0, v187, v0
	v_exp_f32_e32 v191, v1
	v_fma_f32 v1, v79, s77, -v50
	v_add_f32_e32 v0, v188, v0
	v_exp_f32_e32 v192, v1
	v_fma_f32 v1, v194, s77, -v50
	v_add_f32_e32 v0, v189, v0
	v_exp_f32_e32 v194, v1
	v_fma_f32 v1, v16, s77, -v50
	v_add_f32_e32 v0, v190, v0
	v_exp_f32_e32 v178, v1
	v_fma_f32 v1, v17, s77, -v50
	v_add_f32_e32 v0, v191, v0
	v_exp_f32_e32 v179, v1
	v_fma_f32 v1, v18, s77, -v50
	v_add_f32_e32 v0, v192, v0
	v_exp_f32_e32 v180, v1
	v_fma_f32 v1, v19, s77, -v50
	v_add_f32_e32 v0, v194, v0
	v_exp_f32_e32 v181, v1
	v_fma_f32 v1, v20, s77, -v50
	v_add_f32_e32 v0, v178, v0
	v_exp_f32_e32 v182, v1
	v_fma_f32 v1, v21, s77, -v50
	v_add_f32_e32 v0, v179, v0
	v_exp_f32_e32 v183, v1
	v_fma_f32 v1, v22, s77, -v50
	v_add_f32_e32 v0, v180, v0
	v_exp_f32_e32 v184, v1
	v_fma_f32 v1, v23, s77, -v50
	v_add_f32_e32 v0, v181, v0
	v_exp_f32_e32 v185, v1
	v_fma_f32 v1, v24, s77, -v50
	v_add_f32_e32 v0, v182, v0
	v_exp_f32_e32 v73, v1
	v_fma_f32 v1, v25, s77, -v50
	v_add_f32_e32 v0, v183, v0
	v_exp_f32_e32 v74, v1
	v_fma_f32 v1, v26, s77, -v50
	v_add_f32_e32 v0, v184, v0
	v_exp_f32_e32 v75, v1
	v_fma_f32 v1, v27, s77, -v50
	v_add_f32_e32 v0, v185, v0
	v_exp_f32_e32 v77, v1
	v_fma_f32 v1, v28, s77, -v50
	v_add_f32_e32 v0, v73, v0
	v_exp_f32_e32 v78, v1
	v_fma_f32 v1, v29, s77, -v50
	v_add_f32_e32 v0, v74, v0
	v_exp_f32_e32 v79, v1
	v_fma_f32 v1, v30, s77, -v50
	v_add_f32_e32 v0, v75, v0
	v_exp_f32_e32 v176, v1
	v_fma_f32 v1, v31, s77, -v50
	v_add_f32_e32 v0, v77, v0
	v_exp_f32_e32 v177, v1
	v_add_f32_e32 v0, v78, v0
	v_add_f32_e32 v0, v79, v0
	v_add_f32_e32 v0, v176, v0
	v_add_f32_e32 v71, v177, v0
	v_mov_b32_e32 v72, v71
	s_nop 1
	v_permlane32_swap_b32_e32 v71, v72
	v_add_u32_e32 v0, 64, v172
	v_lshrrev_b32_e32 v0, 3, v0
	v_mad_u64_u32 v[64:65], s[0:1], v0, s76, v[168:169]
	v_add_u32_e32 v0, 0x80, v172
	v_lshrrev_b32_e32 v0, 3, v0
	v_mad_u64_u32 v[66:67], s[0:1], v0, s76, v[168:169]
	v_add_u32_e32 v0, 0xc0, v172
	v_lshrrev_b32_e32 v0, 3, v0
	v_mad_u64_u32 v[68:69], s[0:1], v0, s76, v[168:169]
	v_add3_u32 v76, s72, v48, v49
	s_waitcnt vmcnt(19)
	ds_write_b128 v175, v[140:143]
	s_waitcnt vmcnt(18)
	ds_write_b128 v64, v[136:139]
	s_waitcnt vmcnt(17)
	ds_write_b128 v66, v[132:135]
	s_waitcnt vmcnt(16)
	ds_write_b128 v68, v[128:131]
	ds_read_b64_tr_b16 v[0:1], v76
	ds_read_b64_tr_b16 v[2:3], v76 offset:1152
	ds_read_b64_tr_b16 v[10:11], v76 offset:1216
	ds_read_b64_tr_b16 v[8:9], v76 offset:64
	v_cvt_pk_bf16_f32 v4, v51, v52
	v_cvt_pk_bf16_f32 v5, v53, v54
	v_cvt_pk_bf16_f32 v6, v56, v57
	v_cvt_pk_bf16_f32 v7, v58, v59
	ds_read_b64_tr_b16 v[32:33], v76 offset:2304
	ds_read_b64_tr_b16 v[34:35], v76 offset:3456
	s_waitcnt lgkmcnt(4)
	v_mfma_f32_32x32x16_bf16 v[16:31], v[0:3], v[4:7], 0
	ds_read_b64_tr_b16 v[42:43], v76 offset:3520
	ds_read_b64_tr_b16 v[40:41], v76 offset:2368
	v_cvt_pk_bf16_f32 v36, v60, v61
	v_cvt_pk_bf16_f32 v37, v62, v63
	v_cvt_pk_bf16_f32 v38, v193, v195
	v_cvt_pk_bf16_f32 v39, v196, v197
	s_waitcnt lgkmcnt(4)
	v_mfma_f32_32x32x16_bf16 v[0:15], v[8:11], v[4:7], 0
	s_waitcnt lgkmcnt(2)
	v_mfma_f32_32x32x16_bf16 v[16:31], v[32:35], v[36:39], v[16:31]
	s_waitcnt lgkmcnt(0)
	v_mfma_f32_32x32x16_bf16 v[0:15], v[40:43], v[36:39], v[0:15]
	v_lshl_add_u64 v[32:33], s[42:43], 0, v[144:145]
	v_lshl_add_u64 v[34:35], s[42:43], 0, v[154:155]
	global_load_dwordx4 v[48:51], v[32:33], off
	global_load_dwordx4 v[52:55], v[34:35], off
	v_lshl_add_u64 v[32:33], s[42:43], 0, v[156:157]
	v_lshl_add_u64 v[34:35], s[42:43], 0, v[158:159]
	global_load_dwordx4 v[56:59], v[32:33], off
	global_load_dwordx4 v[60:63], v[34:35], off
	v_lshl_add_u64 v[32:33], s[42:43], 0, v[160:161]
	v_lshl_add_u64 v[36:37], s[42:43], 0, v[162:163]
	v_lshl_add_u64 v[40:41], s[42:43], 0, v[164:165]
	v_lshl_add_u64 v[44:45], s[42:43], 0, v[166:167]
	global_load_dwordx4 v[32:35], v[32:33], off
	s_nop 0
	global_load_dwordx4 v[36:39], v[36:37], off
	s_nop 0
	global_load_dwordx4 v[40:43], v[40:41], off
	s_nop 0
	global_load_dwordx4 v[44:47], v[44:45], off
	s_waitcnt vmcnt(23)
	ds_write_b128 v175, v[112:115]
	s_waitcnt vmcnt(22)
	ds_write_b128 v64, v[116:119]
	s_waitcnt vmcnt(21)
	ds_write_b128 v66, v[120:123]
	s_waitcnt vmcnt(20)
	ds_write_b128 v68, v[124:127]
	ds_read_b64_tr_b16 v[116:117], v76
	ds_read_b64_tr_b16 v[118:119], v76 offset:1152
	ds_read_b64_tr_b16 v[120:121], v76 offset:64
	ds_read_b64_tr_b16 v[122:123], v76 offset:1216
	v_cvt_pk_bf16_f32 v112, v198, v199
	v_cvt_pk_bf16_f32 v113, v200, v201
	v_cvt_pk_bf16_f32 v114, v202, v203
	v_cvt_pk_bf16_f32 v115, v204, v205
	s_waitcnt lgkmcnt(2)
	s_nop 0
	v_mfma_f32_32x32x16_bf16 v[16:31], v[116:119], v[112:115], v[16:31]
	s_waitcnt lgkmcnt(0)
	v_mfma_f32_32x32x16_bf16 v[0:15], v[120:123], v[112:115], v[0:15]
	ds_read_b64_tr_b16 v[116:117], v76 offset:2304
	ds_read_b64_tr_b16 v[118:119], v76 offset:3456
	ds_read_b64_tr_b16 v[120:121], v76 offset:2368
	ds_read_b64_tr_b16 v[122:123], v76 offset:3520
	v_cvt_pk_bf16_f32 v112, v206, v207
	v_cvt_pk_bf16_f32 v113, v208, v209
	v_cvt_pk_bf16_f32 v114, v210, v211
	v_cvt_pk_bf16_f32 v115, v212, v213
	s_waitcnt lgkmcnt(2)
	s_nop 0
	v_mfma_f32_32x32x16_bf16 v[16:31], v[116:119], v[112:115], v[16:31]
	s_waitcnt lgkmcnt(0)
	v_mfma_f32_32x32x16_bf16 v[0:15], v[120:123], v[112:115], v[0:15]
	s_waitcnt vmcnt(19)
	ds_write_b128 v175, v[96:99]
	s_waitcnt vmcnt(18)
	ds_write_b128 v64, v[100:103]
	s_waitcnt vmcnt(17)
	ds_write_b128 v66, v[104:107]
	s_waitcnt vmcnt(16)
	ds_write_b128 v68, v[108:111]
	ds_read_b64_tr_b16 v[100:101], v76
	ds_read_b64_tr_b16 v[102:103], v76 offset:1152
	ds_read_b64_tr_b16 v[104:105], v76 offset:64
	ds_read_b64_tr_b16 v[106:107], v76 offset:1216
	v_cvt_pk_bf16_f32 v96, v214, v215
	v_cvt_pk_bf16_f32 v97, v216, v217
	v_cvt_pk_bf16_f32 v98, v218, v219
	v_cvt_pk_bf16_f32 v99, v220, v221
	s_waitcnt lgkmcnt(2)
	s_nop 0
	v_mfma_f32_32x32x16_bf16 v[16:31], v[100:103], v[96:99], v[16:31]
	s_waitcnt lgkmcnt(0)
	v_mfma_f32_32x32x16_bf16 v[0:15], v[104:107], v[96:99], v[0:15]
	ds_read_b64_tr_b16 v[100:101], v76 offset:2304
	ds_read_b64_tr_b16 v[102:103], v76 offset:3456
	ds_read_b64_tr_b16 v[104:105], v76 offset:2368
	ds_read_b64_tr_b16 v[106:107], v76 offset:3520
	v_cvt_pk_bf16_f32 v96, v222, v223
	v_cvt_pk_bf16_f32 v97, v224, v225
	v_cvt_pk_bf16_f32 v98, v226, v227
	v_cvt_pk_bf16_f32 v99, v228, v229
	s_waitcnt lgkmcnt(2)
	s_nop 0
	v_mfma_f32_32x32x16_bf16 v[16:31], v[100:103], v[96:99], v[16:31]
	s_waitcnt lgkmcnt(0)
	v_mfma_f32_32x32x16_bf16 v[0:15], v[104:107], v[96:99], v[0:15]
	s_waitcnt vmcnt(7)
	ds_write_b128 v175, v[48:51]
	s_waitcnt vmcnt(6)
	ds_write_b128 v64, v[52:55]
	s_waitcnt vmcnt(5)
	ds_write_b128 v66, v[56:59]
	s_waitcnt vmcnt(4)
	ds_write_b128 v68, v[60:63]
	ds_read_b64_tr_b16 v[52:53], v76
	ds_read_b64_tr_b16 v[54:55], v76 offset:1152
	ds_read_b64_tr_b16 v[56:57], v76 offset:64
	ds_read_b64_tr_b16 v[58:59], v76 offset:1216
	v_cvt_pk_bf16_f32 v48, v230, v231
	v_cvt_pk_bf16_f32 v49, v232, v233
	v_cvt_pk_bf16_f32 v50, v234, v235
	v_cvt_pk_bf16_f32 v51, v236, v237
	s_waitcnt lgkmcnt(2)
	s_nop 0
	v_mfma_f32_32x32x16_bf16 v[16:31], v[52:55], v[48:51], v[16:31]
	s_waitcnt lgkmcnt(0)
	v_mfma_f32_32x32x16_bf16 v[0:15], v[56:59], v[48:51], v[0:15]
	ds_read_b64_tr_b16 v[52:53], v76 offset:2304
	ds_read_b64_tr_b16 v[54:55], v76 offset:3456
	ds_read_b64_tr_b16 v[56:57], v76 offset:2368
	ds_read_b64_tr_b16 v[58:59], v76 offset:3520
	v_cvt_pk_bf16_f32 v48, v186, v187
	v_cvt_pk_bf16_f32 v49, v188, v189
	v_cvt_pk_bf16_f32 v50, v190, v191
	v_cvt_pk_bf16_f32 v51, v192, v194
	s_waitcnt lgkmcnt(2)
	s_nop 0
	v_mfma_f32_32x32x16_bf16 v[16:31], v[52:55], v[48:51], v[16:31]
	s_waitcnt lgkmcnt(0)
	v_mfma_f32_32x32x16_bf16 v[0:15], v[56:59], v[48:51], v[0:15]
	s_waitcnt vmcnt(3)
	ds_write_b128 v175, v[32:35]
	s_waitcnt vmcnt(2)
	ds_write_b128 v64, v[36:39]
	s_waitcnt vmcnt(1)
	ds_write_b128 v66, v[40:43]
	s_waitcnt vmcnt(0)
	ds_write_b128 v68, v[44:47]
	ds_read_b64_tr_b16 v[36:37], v76
	ds_read_b64_tr_b16 v[38:39], v76 offset:1152
	ds_read_b64_tr_b16 v[40:41], v76 offset:64
	ds_read_b64_tr_b16 v[42:43], v76 offset:1216
	v_cvt_pk_bf16_f32 v32, v178, v179
	v_cvt_pk_bf16_f32 v33, v180, v181
	v_cvt_pk_bf16_f32 v34, v182, v183
	v_cvt_pk_bf16_f32 v35, v184, v185
	s_waitcnt lgkmcnt(2)
	s_nop 0
	v_mfma_f32_32x32x16_bf16 v[16:31], v[36:39], v[32:35], v[16:31]
	s_waitcnt lgkmcnt(0)
	v_mfma_f32_32x32x16_bf16 v[0:15], v[40:43], v[32:35], v[0:15]
	ds_read_b64_tr_b16 v[36:37], v76 offset:2304
	ds_read_b64_tr_b16 v[38:39], v76 offset:3456
	ds_read_b64_tr_b16 v[40:41], v76 offset:2368
	ds_read_b64_tr_b16 v[42:43], v76 offset:3520
	v_cvt_pk_bf16_f32 v32, v73, v74
	v_cvt_pk_bf16_f32 v33, v75, v77
	v_cvt_pk_bf16_f32 v35, v176, v177
	v_cvt_pk_bf16_f32 v34, v78, v79
	s_waitcnt lgkmcnt(2)
	s_nop 0
	v_mfma_f32_32x32x16_bf16 v[16:31], v[36:39], v[32:35], v[16:31]
	v_lshl_add_u64 v[44:45], s[18:19], 0, v[146:147]
	v_lshl_add_u64 v[44:45], s[18:19], 0, v[148:149]
	v_lshl_add_u64 v[44:45], s[18:19], 0, v[150:151]
	v_lshl_add_u64 v[44:45], s[18:19], 0, v[152:153]
	s_waitcnt lgkmcnt(0)
	v_mfma_f32_32x32x16_bf16 v[0:15], v[40:43], v[32:35], v[0:15]
	v_add_f32_e32 v33, v71, v72
	v_div_scale_f32 v32, s[0:1], v33, v33, 1.0
	v_rcp_f32_e32 v34, v32
	s_nop 0
	v_fma_f32 v35, -v32, v34, 1.0
	v_fmac_f32_e32 v34, v35, v34
	v_div_scale_f32 v35, vcc, 1.0, v33, 1.0
	v_mul_f32_e32 v36, v35, v34
	v_fma_f32 v37, -v32, v36, v35
	v_fmac_f32_e32 v36, v37, v34
	v_fma_f32 v32, -v32, v36, v35
	v_log_f32_e32 v35, v33
	v_div_fmas_f32 v32, v32, v34, v36
	v_div_fixup_f32 v32, v32, v33, 1.0
	v_subrev_u32_e32 v33, s84, v174
	v_cndmask_b32_e64 v34, 0, 1, s[54:55]
	v_fmac_f32_e32 v35, 0x3e38aa3b, v70
	v_cmp_ne_u32_e64 s[38:39], 1, v34
	s_andn2_b64 vcc, exec, s[54:55]
	v_lshl_add_u32 v36, v33, 2, 0
	s_cbranch_vccnz .LBB0_358
	v_add_u32_e32 v34, 0x12000, v36
	ds_read_b32 v34, v34
	v_max_f32_e32 v37, v35, v35
	s_waitcnt lgkmcnt(0)
	v_max_f32_e32 v38, v34, v34
	v_max_f32_e32 v37, v38, v37
	v_sub_f32_e32 v38, v34, v37
	v_sub_f32_e32 v39, v35, v37
	v_exp_f32_e32 v38, v38
	v_exp_f32_e32 v39, v39
	s_nop 0
	v_add_f32_e32 v38, v38, v39
	v_log_f32_e32 v38, v38
	s_nop 0
	v_add_f32_e32 v37, v37, v38
	v_sub_f32_e32 v35, v35, v37
	v_exp_f32_e32 v35, v35
	v_sub_f32_e32 v34, v34, v37
	v_exp_f32_e32 v34, v34
	v_mul_f32_e32 v32, v32, v35
	v_mov_b32_e32 v35, v37
	s_branch .LBB0_359

.LBB0_624:
	s_or_b64 exec, exec, s[4:5]
	s_lshr_b32 s0, s97, 6
	s_cmp_eq_u32 s0, 0
	s_cbranch_scc1 .Lw4_skip
	s_mul_i32 s1, s2, 7
	s_add_i32 s0, s0, s1
	s_add_i32 s0, s0, 24575
	v_mbcnt_lo_u32_b32 v106, -1, 0
	v_mbcnt_hi_u32_b32 v106, -1, v106
	v_mov_b32_e32 v108, s0
	v_lshlrev_b32_e32 v106, 4, v106
	v_mov_b32_e32 v107, 0x80403
	v_min_u32_e32 v101, 0xbfff, v108
	v_add_u32_e32 v108, 0x700, v108
	v_lshrrev_b32_e32 v102, 2, v101
	v_and_b32_e32 v101, 3, v101
	v_lshl_add_u32 v101, v102, 3, v101
	v_add_u32_e32 v101, 4, v101
	v_mul_hi_u32 v102, v101, v107
	v_mul_u32_u24_e32 v103, 0x1ff0, v102
	v_and_b32_e32 v104, 7, v102
	v_sub_u32_e32 v103, v101, v103
	v_lshrrev_b32_e32 v102, 3, v102
	v_lshlrev_b32_e32 v104, 23, v104
	v_cmp_ne_u32_e32 vcc, 0, v102
	v_lshl_add_u32 v103, v103, 10, v104
	v_add_u32_e32 v103, v103, v106
	v_lshl_add_u32 v110, v102, 26, v103
	v_add_u32_e32 v103, 0x4000, v103
	v_add_u32_e32 v110, 0x605e000, v110
	s_cbranch_vccnz .Lw4_v0
	global_load_dwordx4 v[170:173], v103, s[48:49] nt
	s_branch .Lw4_d0

.Lw4_d0:
	v_min_u32_e32 v101, 0xbfff, v108
	v_add_u32_e32 v108, 0x700, v108
	v_lshrrev_b32_e32 v102, 2, v101
	v_and_b32_e32 v101, 3, v101
	v_lshl_add_u32 v101, v102, 3, v101
	v_add_u32_e32 v101, 4, v101
	v_mul_hi_u32 v102, v101, v107
	v_mul_u32_u24_e32 v103, 0x1ff0, v102
	v_and_b32_e32 v104, 7, v102
	v_sub_u32_e32 v103, v101, v103
	v_lshrrev_b32_e32 v102, 3, v102
	v_lshlrev_b32_e32 v104, 23, v104
	v_cmp_ne_u32_e32 vcc, 0, v102
	v_lshl_add_u32 v103, v103, 10, v104
	v_add_u32_e32 v103, v103, v106
	v_lshl_add_u32 v111, v102, 26, v103
	v_add_u32_e32 v103, 0x4000, v103
	v_add_u32_e32 v111, 0x605e000, v111
	s_cbranch_vccnz .Lw4_v1
	global_load_dwordx4 v[174:177], v103, s[48:49] nt
	s_branch .Lw4_d1

.Lw4_d1:
	v_min_u32_e32 v101, 0xbfff, v108
	v_add_u32_e32 v108, 0x700, v108
	v_lshrrev_b32_e32 v102, 2, v101
	v_and_b32_e32 v101, 3, v101
	v_lshl_add_u32 v101, v102, 3, v101
	v_add_u32_e32 v101, 4, v101
	v_mul_hi_u32 v102, v101, v107
	v_mul_u32_u24_e32 v103, 0x1ff0, v102
	v_and_b32_e32 v104, 7, v102
	v_sub_u32_e32 v103, v101, v103
	v_lshrrev_b32_e32 v102, 3, v102
	v_lshlrev_b32_e32 v104, 23, v104
	v_cmp_ne_u32_e32 vcc, 0, v102
	v_lshl_add_u32 v103, v103, 10, v104
	v_add_u32_e32 v103, v103, v106
	v_lshl_add_u32 v112, v102, 26, v103
	v_add_u32_e32 v103, 0x4000, v103
	v_add_u32_e32 v112, 0x605e000, v112
	s_cbranch_vccnz .Lw4_v2
	global_load_dwordx4 v[178:181], v103, s[48:49] nt
	s_branch .Lw4_d2

.Lw4_d2:
	v_min_u32_e32 v101, 0xbfff, v108
	v_add_u32_e32 v108, 0x700, v108
	v_lshrrev_b32_e32 v102, 2, v101
	v_and_b32_e32 v101, 3, v101
	v_lshl_add_u32 v101, v102, 3, v101
	v_add_u32_e32 v101, 4, v101
	v_mul_hi_u32 v102, v101, v107
	v_mul_u32_u24_e32 v103, 0x1ff0, v102
	v_and_b32_e32 v104, 7, v102
	v_sub_u32_e32 v103, v101, v103
	v_lshrrev_b32_e32 v102, 3, v102
	v_lshlrev_b32_e32 v104, 23, v104
	v_cmp_ne_u32_e32 vcc, 0, v102
	v_lshl_add_u32 v103, v103, 10, v104
	v_add_u32_e32 v103, v103, v106
	v_lshl_add_u32 v113, v102, 26, v103
	v_add_u32_e32 v103, 0x4000, v103
	v_add_u32_e32 v113, 0x605e000, v113
	s_cbranch_vccnz .Lw4_v3
	global_load_dwordx4 v[182:185], v103, s[48:49] nt
	s_branch .Lw4_d3

.Lw4_d3:
	v_min_u32_e32 v101, 0xbfff, v108
	v_add_u32_e32 v108, 0x700, v108
	v_lshrrev_b32_e32 v102, 2, v101
	v_and_b32_e32 v101, 3, v101
	v_lshl_add_u32 v101, v102, 3, v101
	v_add_u32_e32 v101, 4, v101
	v_mul_hi_u32 v102, v101, v107
	v_mul_u32_u24_e32 v103, 0x1ff0, v102
	v_and_b32_e32 v104, 7, v102
	v_sub_u32_e32 v103, v101, v103
	v_lshrrev_b32_e32 v102, 3, v102
	v_lshlrev_b32_e32 v104, 23, v104
	v_cmp_ne_u32_e32 vcc, 0, v102
	v_lshl_add_u32 v103, v103, 10, v104
	v_add_u32_e32 v103, v103, v106
	v_lshl_add_u32 v114, v102, 26, v103
	v_add_u32_e32 v103, 0x4000, v103
	v_add_u32_e32 v114, 0x605e000, v114
	s_cbranch_vccnz .Lw4_v4
	global_load_dwordx4 v[186:189], v103, s[48:49] nt
	s_branch .Lw4_d4

.Lw4_d4:
	v_min_u32_e32 v101, 0xbfff, v108
	v_add_u32_e32 v108, 0x700, v108
	v_lshrrev_b32_e32 v102, 2, v101
	v_and_b32_e32 v101, 3, v101
	v_lshl_add_u32 v101, v102, 3, v101
	v_add_u32_e32 v101, 4, v101
	v_mul_hi_u32 v102, v101, v107
	v_mul_u32_u24_e32 v103, 0x1ff0, v102
	v_and_b32_e32 v104, 7, v102
	v_sub_u32_e32 v103, v101, v103
	v_lshrrev_b32_e32 v102, 3, v102
	v_lshlrev_b32_e32 v104, 23, v104
	v_cmp_ne_u32_e32 vcc, 0, v102
	v_lshl_add_u32 v103, v103, 10, v104
	v_add_u32_e32 v103, v103, v106
	v_lshl_add_u32 v115, v102, 26, v103
	v_add_u32_e32 v103, 0x4000, v103
	v_add_u32_e32 v115, 0x605e000, v115
	s_cbranch_vccnz .Lw4_v5
	global_load_dwordx4 v[190:193], v103, s[48:49] nt
	s_branch .Lw4_d5

.Lw4_d5:
	v_min_u32_e32 v101, 0xbfff, v108
	v_add_u32_e32 v108, 0x700, v108
	v_lshrrev_b32_e32 v102, 2, v101
	v_and_b32_e32 v101, 3, v101
	v_lshl_add_u32 v101, v102, 3, v101
	v_add_u32_e32 v101, 4, v101
	v_mul_hi_u32 v102, v101, v107
	v_mul_u32_u24_e32 v103, 0x1ff0, v102
	v_and_b32_e32 v104, 7, v102
	v_sub_u32_e32 v103, v101, v103
	v_lshrrev_b32_e32 v102, 3, v102
	v_lshlrev_b32_e32 v104, 23, v104
	v_cmp_ne_u32_e32 vcc, 0, v102
	v_lshl_add_u32 v103, v103, 10, v104
	v_add_u32_e32 v103, v103, v106
	v_lshl_add_u32 v116, v102, 26, v103
	v_add_u32_e32 v103, 0x4000, v103
	v_add_u32_e32 v116, 0x605e000, v116
	s_cbranch_vccnz .Lw4_v6
	global_load_dwordx4 v[194:197], v103, s[48:49] nt
	s_branch .Lw4_d6

.Lw4_d6:
	v_min_u32_e32 v101, 0xbfff, v108
	v_add_u32_e32 v108, 0x700, v108
	v_lshrrev_b32_e32 v102, 2, v101
	v_and_b32_e32 v101, 3, v101
	v_lshl_add_u32 v101, v102, 3, v101
	v_add_u32_e32 v101, 4, v101
	v_mul_hi_u32 v102, v101, v107
	v_mul_u32_u24_e32 v103, 0x1ff0, v102
	v_and_b32_e32 v104, 7, v102
	v_sub_u32_e32 v103, v101, v103
	v_lshrrev_b32_e32 v102, 3, v102
	v_lshlrev_b32_e32 v104, 23, v104
	v_cmp_ne_u32_e32 vcc, 0, v102
	v_lshl_add_u32 v103, v103, 10, v104
	v_add_u32_e32 v103, v103, v106
	v_lshl_add_u32 v117, v102, 26, v103
	v_add_u32_e32 v103, 0x4000, v103
	v_add_u32_e32 v117, 0x605e000, v117
	s_cbranch_vccnz .Lw4_v7
	global_load_dwordx4 v[198:201], v103, s[48:49] nt
	s_branch .Lw4_d7

.Lw4_d7:
	v_min_u32_e32 v101, 0xbfff, v108
	v_add_u32_e32 v108, 0x700, v108
	v_lshrrev_b32_e32 v102, 2, v101
	v_and_b32_e32 v101, 3, v101
	v_lshl_add_u32 v101, v102, 3, v101
	v_add_u32_e32 v101, 4, v101
	v_mul_hi_u32 v102, v101, v107
	v_mul_u32_u24_e32 v103, 0x1ff0, v102
	v_and_b32_e32 v104, 7, v102
	v_sub_u32_e32 v103, v101, v103
	v_lshrrev_b32_e32 v102, 3, v102
	v_lshlrev_b32_e32 v104, 23, v104
	v_cmp_ne_u32_e32 vcc, 0, v102
	v_lshl_add_u32 v103, v103, 10, v104
	v_add_u32_e32 v103, v103, v106
	v_lshl_add_u32 v118, v102, 26, v103
	v_add_u32_e32 v103, 0x4000, v103
	v_add_u32_e32 v118, 0x605e000, v118
	s_cbranch_vccnz .Lw4_v8
	global_load_dwordx4 v[202:205], v103, s[48:49] nt
	s_branch .Lw4_d8

.Lw4_d8:
	v_min_u32_e32 v101, 0xbfff, v108
	v_add_u32_e32 v108, 0x700, v108
	v_lshrrev_b32_e32 v102, 2, v101
	v_and_b32_e32 v101, 3, v101
	v_lshl_add_u32 v101, v102, 3, v101
	v_add_u32_e32 v101, 4, v101
	v_mul_hi_u32 v102, v101, v107
	v_mul_u32_u24_e32 v103, 0x1ff0, v102
	v_and_b32_e32 v104, 7, v102
	v_sub_u32_e32 v103, v101, v103
	v_lshrrev_b32_e32 v102, 3, v102
	v_lshlrev_b32_e32 v104, 23, v104
	v_cmp_ne_u32_e32 vcc, 0, v102
	v_lshl_add_u32 v103, v103, 10, v104
	v_add_u32_e32 v103, v103, v106
	v_lshl_add_u32 v119, v102, 26, v103
	v_add_u32_e32 v103, 0x4000, v103
	v_add_u32_e32 v119, 0x605e000, v119
	s_cbranch_vccnz .Lw4_v9
	global_load_dwordx4 v[206:209], v103, s[48:49] nt
	s_branch .Lw4_d9

.Lw4_d9:
	v_min_u32_e32 v101, 0xbfff, v108
	v_add_u32_e32 v108, 0x700, v108
	v_lshrrev_b32_e32 v102, 2, v101
	v_and_b32_e32 v101, 3, v101
	v_lshl_add_u32 v101, v102, 3, v101
	v_add_u32_e32 v101, 4, v101
	v_mul_hi_u32 v102, v101, v107
	v_mul_u32_u24_e32 v103, 0x1ff0, v102
	v_and_b32_e32 v104, 7, v102
	v_sub_u32_e32 v103, v101, v103
	v_lshrrev_b32_e32 v102, 3, v102
	v_lshlrev_b32_e32 v104, 23, v104
	v_cmp_ne_u32_e32 vcc, 0, v102
	v_lshl_add_u32 v103, v103, 10, v104
	v_add_u32_e32 v103, v103, v106
	v_lshl_add_u32 v120, v102, 26, v103
	v_add_u32_e32 v103, 0x4000, v103
	v_add_u32_e32 v120, 0x605e000, v120
	s_cbranch_vccnz .Lw4_v10
	global_load_dwordx4 v[210:213], v103, s[48:49] nt
	s_branch .Lw4_d10

.Lw4_d10:
	v_min_u32_e32 v101, 0xbfff, v108
	v_add_u32_e32 v108, 0x700, v108
	v_lshrrev_b32_e32 v102, 2, v101
	v_and_b32_e32 v101, 3, v101
	v_lshl_add_u32 v101, v102, 3, v101
	v_add_u32_e32 v101, 4, v101
	v_mul_hi_u32 v102, v101, v107
	v_mul_u32_u24_e32 v103, 0x1ff0, v102
	v_and_b32_e32 v104, 7, v102
	v_sub_u32_e32 v103, v101, v103
	v_lshrrev_b32_e32 v102, 3, v102
	v_lshlrev_b32_e32 v104, 23, v104
	v_cmp_ne_u32_e32 vcc, 0, v102
	v_lshl_add_u32 v103, v103, 10, v104
	v_add_u32_e32 v103, v103, v106
	v_lshl_add_u32 v121, v102, 26, v103
	v_add_u32_e32 v103, 0x4000, v103
	v_add_u32_e32 v121, 0x605e000, v121
	s_cbranch_vccnz .Lw4_v11
	global_load_dwordx4 v[214:217], v103, s[48:49] nt
	s_branch .Lw4_d11

.Lw4_d11:
	v_min_u32_e32 v101, 0xbfff, v108
	v_add_u32_e32 v108, 0x700, v108
	v_lshrrev_b32_e32 v102, 2, v101
	v_and_b32_e32 v101, 3, v101
	v_lshl_add_u32 v101, v102, 3, v101
	v_add_u32_e32 v101, 4, v101
	v_mul_hi_u32 v102, v101, v107
	v_mul_u32_u24_e32 v103, 0x1ff0, v102
	v_and_b32_e32 v104, 7, v102
	v_sub_u32_e32 v103, v101, v103
	v_lshrrev_b32_e32 v102, 3, v102
	v_lshlrev_b32_e32 v104, 23, v104
	v_cmp_ne_u32_e32 vcc, 0, v102
	v_lshl_add_u32 v103, v103, 10, v104
	v_add_u32_e32 v103, v103, v106
	v_lshl_add_u32 v122, v102, 26, v103
	v_add_u32_e32 v103, 0x4000, v103
	v_add_u32_e32 v122, 0x605e000, v122
	s_cbranch_vccnz .Lw4_v12
	global_load_dwordx4 v[218:221], v103, s[48:49] nt
	s_branch .Lw4_d12

.Lw4_d12:
	v_min_u32_e32 v101, 0xbfff, v108
	v_add_u32_e32 v108, 0x700, v108
	v_lshrrev_b32_e32 v102, 2, v101
	v_and_b32_e32 v101, 3, v101
	v_lshl_add_u32 v101, v102, 3, v101
	v_add_u32_e32 v101, 4, v101
	v_mul_hi_u32 v102, v101, v107
	v_mul_u32_u24_e32 v103, 0x1ff0, v102
	v_and_b32_e32 v104, 7, v102
	v_sub_u32_e32 v103, v101, v103
	v_lshrrev_b32_e32 v102, 3, v102
	v_lshlrev_b32_e32 v104, 23, v104
	v_cmp_ne_u32_e32 vcc, 0, v102
	v_lshl_add_u32 v103, v103, 10, v104
	v_add_u32_e32 v103, v103, v106
	v_lshl_add_u32 v123, v102, 26, v103
	v_add_u32_e32 v103, 0x4000, v103
	v_add_u32_e32 v123, 0x605e000, v123
	s_cbranch_vccnz .Lw4_v13
	global_load_dwordx4 v[222:225], v103, s[48:49] nt
	s_branch .Lw4_d13

.Lw4_skip:
	v_readlane_b32 s34, v238, 15
	s_cmp_gt_i32 s2, 63
	v_readlane_b32 s35, v238, 16
	s_waitcnt lgkmcnt(0)
	s_barrier
	s_cbranch_scc1 .LBB0_648
	v_mbcnt_lo_u32_b32 v23, -1, 0
	v_mbcnt_hi_u32_b32 v23, -1, v23
	s_lshl_b32 s4, s2, 5
	v_add_u32_e32 v22, s97, v23
	v_ashrrev_i32_e32 v24, 6, v22
	v_and_b32_e32 v25, 15, v23
	v_lshlrev_b32_e32 v0, 8, v24
	v_or_b32_e32 v2, s4, v25
	v_ashrrev_i32_e32 v1, 31, v0
	v_ashrrev_i32_e32 v3, 31, v2
	v_lshlrev_b64 v[2:3], 12, v[2:3]
	v_lshlrev_b64 v[16:17], 1, v[0:1]
	v_and_b32_e32 v0, 48, v23
	v_or_b32_e32 v2, v2, v0
	v_lshl_or_b32 v0, v25, 12, v0
	v_mov_b32_e32 v1, 0
	v_lshl_add_u64 v[18:19], s[92:93], 0, v[2:3]
	v_lshl_add_u64 v[20:21], s[92:93], 0, v[0:1]
	s_movk_i32 s5, 0xffe0
	s_mov_b32 s6, 0xc800000
	s_mov_b32 s7, 0xc810000
	s_mov_b32 s8, 0x1a00000
	s_mov_b32 s9, 0x1a10000
	s_mov_b64 s[0:1], 0x100
	v_mov_b32_e32 v0, v1
	v_mov_b32_e32 v2, v1
	v_mov_b32_e32 v3, v1
	v_mov_b32_e32 v8, v1
	v_mov_b32_e32 v9, v1
	v_mov_b32_e32 v10, v1
	v_mov_b32_e32 v11, v1
	v_mov_b32_e32 v4, v1
	v_mov_b32_e32 v5, v1
	v_mov_b32_e32 v6, v1
	v_mov_b32_e32 v7, v1
	v_mov_b32_e32 v12, v1
	v_mov_b32_e32 v13, v1
	v_mov_b32_e32 v14, v1
	v_mov_b32_e32 v15, v1
